# attention: QK accumulator -mhat init uses v_mov_b64 (8 fewer VALU per step)
# speedup vs baseline: 1.0056x; 1.0056x over previous
.LBB0_1277:
	s_lshl_b32 s18, s23, 1
	v_add_u32_e32 v237, s18, v214
	ds_read_b64_tr_b16 v[192:193], v237 offset:24576
	v_xor_b32_e32 v96, 0x80000000, v235
	v_mov_b32_e32 v97, v96
	v_mov_b64_e32 v[98:99], v[96:97]
	v_mov_b64_e32 v[100:101], v[96:97]
	v_mov_b64_e32 v[102:103], v[96:97]
	v_mov_b64_e32 v[104:105], v[96:97]
	v_mov_b64_e32 v[106:107], v[96:97]
	v_mov_b64_e32 v[108:109], v[96:97]
	v_mov_b64_e32 v[110:111], v[96:97]
	v_add_f32_e32 v112, v80, v81
	v_add_f32_e32 v112, v82, v112
	v_add_f32_e32 v112, v83, v112
	v_add_f32_e32 v112, v84, v112
	v_add_f32_e32 v128, v85, v112
	s_waitcnt lgkmcnt(8)
	v_mfma_f32_32x32x16_bf16 v[112:127], v[188:191], v[156:159], v[96:111]
	v_cvt_pk_bf16_f32 v148, v80, v81
	v_cvt_pk_bf16_f32 v149, v82, v83
	ds_read_b64_tr_b16 v[194:195], v237 offset:25088
	s_waitcnt lgkmcnt(8)
	v_mfma_f32_32x32x16_bf16 v[96:111], v[184:187], v[156:159], v[96:111]
	v_add_f32_e32 v80, v86, v128
	v_add_f32_e32 v80, v87, v80
	v_add_f32_e32 v80, v88, v80
	v_add_f32_e32 v82, v89, v80
	v_cvt_pk_bf16_f32 v150, v84, v85
	v_cvt_pk_bf16_f32 v151, v86, v87
	ds_read_b64_tr_b16 v[80:81], v237 offset:28672
	s_waitcnt lgkmcnt(8)
	v_mfma_f32_32x32x16_bf16 v[112:127], v[180:183], v[152:155], v[112:127]
	v_add_f32_e32 v82, v90, v82
	v_add_f32_e32 v82, v91, v82
	v_add_f32_e32 v82, v92, v82
	v_add_f32_e32 v84, v93, v82
	v_cvt_pk_bf16_f32 v140, v88, v89
	v_cvt_pk_bf16_f32 v141, v90, v91
	ds_read_b64_tr_b16 v[82:83], v237 offset:29184
	s_waitcnt lgkmcnt(8)
	v_mfma_f32_32x32x16_bf16 v[96:111], v[176:179], v[152:155], v[96:111]
	v_add_f32_e32 v84, v94, v84
	v_add_f32_e32 v84, v95, v84
	v_add_f32_e32 v84, v64, v84
	v_add_f32_e32 v86, v65, v84
	v_cvt_pk_bf16_f32 v142, v92, v93
	v_cvt_pk_bf16_f32 v143, v94, v95
	ds_read_b64_tr_b16 v[84:85], v237 offset:32768
	s_waitcnt lgkmcnt(8)
	v_mfma_f32_32x32x16_bf16 v[112:127], v[172:175], v[144:147], v[112:127]
	v_add_f32_e32 v86, v66, v86
	v_add_f32_e32 v86, v67, v86
	v_add_f32_e32 v86, v68, v86
	v_add_f32_e32 v88, v69, v86
	v_cvt_pk_bf16_f32 v132, v64, v65
	v_cvt_pk_bf16_f32 v133, v66, v67
	ds_read_b64_tr_b16 v[86:87], v237 offset:33280
	s_waitcnt lgkmcnt(8)
	v_mfma_f32_32x32x16_bf16 v[96:111], v[168:171], v[144:147], v[96:111]
	v_add_f32_e32 v64, v70, v88
	v_add_f32_e32 v64, v71, v64
	v_add_f32_e32 v64, v72, v64
	v_add_f32_e32 v66, v73, v64
	v_cvt_pk_bf16_f32 v134, v68, v69
	v_cvt_pk_bf16_f32 v135, v70, v71
	ds_read_b64_tr_b16 v[64:65], v237 offset:36864
	s_waitcnt lgkmcnt(8)
	v_mfma_f32_32x32x16_bf16 v[112:127], v[164:167], v[136:139], v[112:127]
	v_add_f32_e32 v66, v74, v66
	v_add_f32_e32 v66, v75, v66
	v_add_f32_e32 v66, v76, v66
	v_add_f32_e32 v68, v77, v66
	v_cvt_pk_bf16_f32 v128, v72, v73
	v_cvt_pk_bf16_f32 v129, v74, v75
	ds_read_b64_tr_b16 v[66:67], v237 offset:37376
	s_waitcnt lgkmcnt(8)
	v_mfma_f32_32x32x16_bf16 v[96:111], v[160:163], v[136:139], v[96:111]
	v_add_f32_e32 v68, v78, v68
	v_add_f32_e32 v68, v79, v68
	v_add_f32_e32 v70, 0, v68
	v_cvt_pk_bf16_f32 v130, v76, v77
	v_cvt_pk_bf16_f32 v131, v78, v79
	s_movk_i32 s30, 0xc000
	v_lshl_add_u64 v[68:69], v[206:207], 0, s[44:45]
	s_add_i32 s18, s86, s89
	s_mov_b32 s31, -1
	s_mov_b32 s23, m0
	s_mov_b32 m0, s18
	s_nop 0
	global_load_lds_dwordx4 v[68:69], off
	s_mov_b32 m0, s23
	v_lshl_add_u64 v[68:69], v[204:205], 0, s[30:31]
	s_lshl_b32 s18, s37, 1
	s_add_i32 s18, s18, s90
	s_mov_b32 s23, m0
	s_mov_b32 m0, s18
	s_nop 0
	global_load_lds_dwordx4 v[68:69], off
	s_mov_b32 m0, s23
	v_lshl_add_u64 v[68:69], v[204:205], 0, s[44:45]
	s_addk_i32 s18, 0x2000
	s_mov_b32 s23, m0
	s_mov_b32 m0, s18
	s_nop 0
	global_load_lds_dwordx4 v[68:69], off
	s_mov_b32 m0, s23
	v_max_f32_e32 v68, v113, v113
	v_max_f32_e32 v69, v112, v112
	v_max_f32_e32 v68, v69, v68
	v_max3_f32 v69, v114, v115, v97
	v_max3_f32 v68, v68, v96, v98
	v_max3_f32 v68, v68, v99, v116
	v_max3_f32 v69, v69, v118, v119
	v_max3_f32 v68, v68, v117, v100
	v_max3_f32 v69, v69, v102, v103
	v_max3_f32 v68, v68, v101, v120
	v_max3_f32 v69, v69, v122, v123
	v_max3_f32 v68, v68, v121, v104
	v_max3_f32 v69, v69, v106, v107
	v_max3_f32 v68, v68, v105, v124
	v_max3_f32 v69, v69, v126, v127
	v_max3_f32 v68, v68, v125, v108
	v_max3_f32 v69, v69, v110, v111
	v_max3_f32 v68, v68, v109, v69
	v_mov_b32_e32 v69, v68
	s_nop 1
	v_permlane32_swap_b32_e32 v68, v69
	v_max_f32_e32 v69, v69, v69
	v_max_f32_e32 v68, v68, v68
	v_max_f32_e32 v68, v68, v69
	v_cmp_lt_f32_e32 vcc, s71, v68
	s_cmp_lg_u64 vcc, 0
	v_add_f32_e32 v236, v236, v70
	s_cselect_b64 s[50:51], -1, 0
	s_cbranch_vccnz .LBB0_1285

.LBB0_1280:
	s_add_i32 s18, s37, 0x2000
	s_lshl_b32 s23, s86, 1
	v_add_u32_e32 v237, s23, v214
	ds_read_b64_tr_b16 v[180:181], v237 offset:24576
	v_xor_b32_e32 v64, 0x80000000, v235
	v_mov_b32_e32 v65, v64
	s_cmpk_lg_i32 s37, 0x4000
	v_mov_b64_e32 v[66:67], v[64:65]
	v_mov_b64_e32 v[68:69], v[64:65]
	v_mov_b64_e32 v[70:71], v[64:65]
	v_mov_b64_e32 v[72:73], v[64:65]
	v_mov_b64_e32 v[74:75], v[64:65]
	v_mov_b64_e32 v[76:77], v[64:65]
	v_mov_b64_e32 v[78:79], v[64:65]
	s_cselect_b32 s86, s18, 0
	v_add_f32_e32 v80, v112, v113
	v_add_f32_e32 v80, v114, v80
	v_add_f32_e32 v80, v115, v80
	v_add_f32_e32 v80, v116, v80
	v_add_f32_e32 v128, v117, v80
	s_waitcnt lgkmcnt(8)
	v_mfma_f32_32x32x16_bf16 v[80:95], v[192:195], v[156:159], v[64:79]
	v_cvt_pk_bf16_f32 v148, v112, v113
	v_cvt_pk_bf16_f32 v149, v114, v115
	ds_read_b64_tr_b16 v[182:183], v237 offset:25088
	s_waitcnt lgkmcnt(8)
	v_mfma_f32_32x32x16_bf16 v[64:79], v[188:191], v[156:159], v[64:79]
	v_add_f32_e32 v112, v118, v128
	v_add_f32_e32 v112, v119, v112
	v_add_f32_e32 v112, v120, v112
	v_add_f32_e32 v114, v121, v112
	v_cvt_pk_bf16_f32 v150, v116, v117
	v_cvt_pk_bf16_f32 v151, v118, v119
	ds_read_b64_tr_b16 v[112:113], v237 offset:28672
	s_waitcnt lgkmcnt(8)
	v_mfma_f32_32x32x16_bf16 v[80:95], v[184:187], v[152:155], v[80:95]
	v_add_f32_e32 v114, v122, v114
	v_add_f32_e32 v114, v123, v114
	v_add_f32_e32 v114, v124, v114
	v_add_f32_e32 v116, v125, v114
	v_cvt_pk_bf16_f32 v140, v120, v121
	v_cvt_pk_bf16_f32 v141, v122, v123
	ds_read_b64_tr_b16 v[114:115], v237 offset:29184
	s_waitcnt lgkmcnt(8)
	v_mfma_f32_32x32x16_bf16 v[64:79], v[176:179], v[152:155], v[64:79]
	v_add_f32_e32 v116, v126, v116
	v_add_f32_e32 v116, v127, v116
	v_add_f32_e32 v116, v96, v116
	v_add_f32_e32 v118, v97, v116
	v_cvt_pk_bf16_f32 v142, v124, v125
	v_cvt_pk_bf16_f32 v143, v126, v127
	ds_read_b64_tr_b16 v[116:117], v237 offset:32768
	s_waitcnt lgkmcnt(8)
	v_mfma_f32_32x32x16_bf16 v[80:95], v[172:175], v[144:147], v[80:95]
	v_add_f32_e32 v118, v98, v118
	v_add_f32_e32 v118, v99, v118
	v_add_f32_e32 v118, v100, v118
	v_add_f32_e32 v120, v101, v118
	v_cvt_pk_bf16_f32 v132, v96, v97
	v_cvt_pk_bf16_f32 v133, v98, v99
	ds_read_b64_tr_b16 v[118:119], v237 offset:33280
	s_waitcnt lgkmcnt(8)
	v_mfma_f32_32x32x16_bf16 v[64:79], v[168:171], v[144:147], v[64:79]
	v_add_f32_e32 v96, v102, v120
	v_add_f32_e32 v96, v103, v96
	v_add_f32_e32 v96, v104, v96
	v_add_f32_e32 v98, v105, v96
	v_cvt_pk_bf16_f32 v134, v100, v101
	v_cvt_pk_bf16_f32 v135, v102, v103
	ds_read_b64_tr_b16 v[96:97], v237 offset:36864
	s_waitcnt lgkmcnt(8)
	v_mfma_f32_32x32x16_bf16 v[80:95], v[164:167], v[136:139], v[80:95]
	v_add_f32_e32 v98, v106, v98
	v_add_f32_e32 v98, v107, v98
	v_add_f32_e32 v98, v108, v98
	v_add_f32_e32 v100, v109, v98
	v_cvt_pk_bf16_f32 v128, v104, v105
	v_cvt_pk_bf16_f32 v129, v106, v107
	ds_read_b64_tr_b16 v[98:99], v237 offset:37376
	s_waitcnt lgkmcnt(8)
	v_mfma_f32_32x32x16_bf16 v[64:79], v[160:163], v[136:139], v[64:79]
	v_add_f32_e32 v100, v110, v100
	v_add_f32_e32 v100, v111, v100
	v_add_f32_e32 v102, 0, v100
	v_cvt_pk_bf16_f32 v130, v108, v109
	v_cvt_pk_bf16_f32 v131, v110, v111
	s_add_i32 s18, s37, s89
	s_mov_b32 s23, m0
	s_mov_b32 m0, s18
	s_nop 0
	global_load_lds_dwordx4 v[206:207], off
	s_mov_b32 m0, s23
	s_lshl_b32 s18, s86, 1
	s_add_i32 s18, s18, s90
	s_mov_b32 s23, m0
	s_mov_b32 m0, s18
	s_nop 0
	global_load_lds_dwordx4 v[204:205], off
	s_mov_b32 m0, s23
	v_lshl_add_u64 v[100:101], v[204:205], 0, s[14:15]
	s_addk_i32 s18, 0x2000
	s_mov_b32 s23, m0
	s_mov_b32 m0, s18
	s_nop 0
	global_load_lds_dwordx4 v[100:101], off
	s_mov_b32 m0, s23
	v_max_f32_e32 v100, v81, v81
	v_max_f32_e32 v101, v80, v80
	v_max_f32_e32 v100, v101, v100
	v_max3_f32 v101, v82, v83, v65
	v_max3_f32 v100, v100, v64, v66
	v_max3_f32 v100, v100, v67, v84
	v_max3_f32 v101, v101, v86, v87
	v_max3_f32 v100, v100, v85, v68
	v_max3_f32 v101, v101, v70, v71
	v_max3_f32 v100, v100, v69, v88
	v_max3_f32 v101, v101, v90, v91
	v_max3_f32 v100, v100, v89, v72
	v_max3_f32 v101, v101, v74, v75
	v_max3_f32 v100, v100, v73, v92
	v_max3_f32 v101, v101, v94, v95
	v_max3_f32 v100, v100, v93, v76
	v_max3_f32 v101, v101, v78, v79
	v_max3_f32 v100, v100, v77, v101
	v_mov_b32_e32 v101, v100
	s_nop 1
	v_permlane32_swap_b32_e32 v100, v101
	v_max_f32_e32 v101, v101, v101
	v_max_f32_e32 v100, v100, v100
	v_max_f32_e32 v100, v100, v101
	v_cmp_lt_f32_e32 vcc, s71, v100
	s_cmp_lg_u64 vcc, 0
	v_add_f32_e32 v236, v236, v102
	s_cselect_b64 s[50:51], -1, 0
	s_cbranch_vccnz .LBB0_1288

;   #define RESC() do{ if(resc){ asm volatile("s_waitcnt lgkmcnt(0)":::"memory"); \
;       _Pragma("unroll") for(int d_=0;d_<4;++d_) _Pragma("unroll") for(int r=0;r<16;++r)o[d_][r]*=wsf[crow(r,hi)]; } }while(0)
;   #define ROT() do{sl_prev=sl_cur;sl_cur=sl_next;sl_next=(sl_next==(NSLOT-1)*SLOTB)?0:sl_next+SLOTB;}while(0)
;   #define ENDW(tt) do{ if((tt)+3<NT){WAIT_BAR(3);} else if((tt)+2<NT){WAIT_BAR(2);} else {WAIT_BAR(0);} }while(0)
; template<int THRL> __device__ __forceinline__ void attn_unit(int b,int hc,int qb,const bf16*Q,const bf16*__restrict__ K,const bf16*__restrict__ V,bf16*O,char*shm){
;     ...
;   for(;t+1<NT;t+=2){
;     STEP(pB0,pB1,pA0,pA1,t,(t+3<NT),(t+1<NT),(t+1<NT));       ENDW(t);   RESC(); ROT();
;     STEP(pA0,pA1,pB0,pB1,t+1,(t+4<NT),(t+2<NT),(t+2<NT));     ENDW(t+1); RESC(); ROT();
.LBB0_1296:
	s_lshl_b32 s0, s37, 1
	v_add_u32_e32 v237, s0, v214
	ds_read_b64_tr_b16 v[192:193], v237 offset:24576
	v_xor_b32_e32 v96, 0x80000000, v235
	v_mov_b32_e32 v97, v96
	v_mov_b64_e32 v[98:99], v[96:97]
	v_mov_b64_e32 v[100:101], v[96:97]
	v_mov_b64_e32 v[102:103], v[96:97]
	v_mov_b64_e32 v[104:105], v[96:97]
	v_mov_b64_e32 v[106:107], v[96:97]
	v_mov_b64_e32 v[108:109], v[96:97]
	v_mov_b64_e32 v[110:111], v[96:97]
	v_add_f32_e32 v112, v80, v81
	v_add_f32_e32 v112, v82, v112
	v_add_f32_e32 v112, v83, v112
	v_add_f32_e32 v112, v84, v112
	v_add_f32_e32 v128, v85, v112
	s_waitcnt lgkmcnt(8)
	v_mfma_f32_32x32x16_bf16 v[112:127], v[188:191], v[156:159], v[96:111]
	v_cvt_pk_bf16_f32 v148, v80, v81
	v_cvt_pk_bf16_f32 v149, v82, v83
	ds_read_b64_tr_b16 v[194:195], v237 offset:25088
	s_waitcnt lgkmcnt(8)
	v_mfma_f32_32x32x16_bf16 v[96:111], v[184:187], v[156:159], v[96:111]
	v_add_f32_e32 v80, v86, v128
	v_add_f32_e32 v80, v87, v80
	v_add_f32_e32 v80, v88, v80
	v_add_f32_e32 v82, v89, v80
	v_cvt_pk_bf16_f32 v150, v84, v85
	v_cvt_pk_bf16_f32 v151, v86, v87
	ds_read_b64_tr_b16 v[80:81], v237 offset:28672
	s_waitcnt lgkmcnt(8)
	v_mfma_f32_32x32x16_bf16 v[112:127], v[180:183], v[152:155], v[112:127]
	v_add_f32_e32 v82, v90, v82
	v_add_f32_e32 v82, v91, v82
	v_add_f32_e32 v82, v92, v82
	v_add_f32_e32 v84, v93, v82
	v_cvt_pk_bf16_f32 v140, v88, v89
	v_cvt_pk_bf16_f32 v141, v90, v91
	ds_read_b64_tr_b16 v[82:83], v237 offset:29184
	s_waitcnt lgkmcnt(8)
	v_mfma_f32_32x32x16_bf16 v[96:111], v[176:179], v[152:155], v[96:111]
	v_add_f32_e32 v84, v94, v84
	v_add_f32_e32 v84, v95, v84
	v_add_f32_e32 v84, v64, v84
	v_add_f32_e32 v86, v65, v84
	v_cvt_pk_bf16_f32 v142, v92, v93
	v_cvt_pk_bf16_f32 v143, v94, v95
	ds_read_b64_tr_b16 v[84:85], v237 offset:32768
	s_waitcnt lgkmcnt(8)
	v_mfma_f32_32x32x16_bf16 v[112:127], v[172:175], v[144:147], v[112:127]
	v_add_f32_e32 v86, v66, v86
	v_add_f32_e32 v86, v67, v86
	v_add_f32_e32 v86, v68, v86
	v_add_f32_e32 v88, v69, v86
	v_cvt_pk_bf16_f32 v132, v64, v65
	v_cvt_pk_bf16_f32 v133, v66, v67
	ds_read_b64_tr_b16 v[86:87], v237 offset:33280
	s_waitcnt lgkmcnt(8)
	v_mfma_f32_32x32x16_bf16 v[96:111], v[168:171], v[144:147], v[96:111]
	v_add_f32_e32 v64, v70, v88
	v_add_f32_e32 v64, v71, v64
	v_add_f32_e32 v64, v72, v64
	v_add_f32_e32 v66, v73, v64
	v_cvt_pk_bf16_f32 v134, v68, v69
	v_cvt_pk_bf16_f32 v135, v70, v71
	ds_read_b64_tr_b16 v[64:65], v237 offset:36864
	s_waitcnt lgkmcnt(8)
	v_mfma_f32_32x32x16_bf16 v[112:127], v[164:167], v[136:139], v[112:127]
	v_add_f32_e32 v66, v74, v66
	v_add_f32_e32 v66, v75, v66
	v_add_f32_e32 v66, v76, v66
	v_add_f32_e32 v68, v77, v66
	v_cvt_pk_bf16_f32 v128, v72, v73
	v_cvt_pk_bf16_f32 v129, v74, v75
	ds_read_b64_tr_b16 v[66:67], v237 offset:37376
	s_waitcnt lgkmcnt(8)
	v_mfma_f32_32x32x16_bf16 v[96:111], v[160:163], v[136:139], v[96:111]
	v_add_f32_e32 v68, v78, v68
	v_add_f32_e32 v68, v79, v68
	v_add_f32_e32 v68, 0, v68
	v_cvt_pk_bf16_f32 v130, v76, v77
	v_cvt_pk_bf16_f32 v131, v78, v79
	s_add_i32 s0, s38, 1
	s_cmp_ge_i32 s0, s91
	s_cselect_b64 s[50:51], -1, 0
	s_and_b64 vcc, exec, s[50:51]
	s_cbranch_vccnz .LBB0_1298
	s_add_i32 s0, s86, s89
	v_lshl_add_u64 v[70:71], v[202:203], 0, s[44:45]
	s_mov_b32 s1, m0
	s_mov_b32 m0, s0
	s_nop 0
	global_load_lds_dwordx4 v[70:71], off
	s_mov_b32 m0, s1

;   #define RESC() do{ if(resc){ asm volatile("s_waitcnt lgkmcnt(0)":::"memory"); \
;       _Pragma("unroll") for(int d_=0;d_<4;++d_) _Pragma("unroll") for(int r=0;r<16;++r)o[d_][r]*=wsf[crow(r,hi)]; } }while(0)
;   #define ROT() do{sl_prev=sl_cur;sl_cur=sl_next;sl_next=(sl_next==(NSLOT-1)*SLOTB)?0:sl_next+SLOTB;}while(0)
;   #define ENDW(tt) do{ if((tt)+3<NT){WAIT_BAR(3);} else if((tt)+2<NT){WAIT_BAR(2);} else {WAIT_BAR(0);} }while(0)
; template<int THRL> __device__ __forceinline__ void attn_unit(int b,int hc,int qb,const bf16*Q,const bf16*__restrict__ K,const bf16*__restrict__ V,bf16*O,char*shm){
;     ...
;   for(;t+1<NT;t+=2){
;     STEP(pB0,pB1,pA0,pA1,t,(t+3<NT),(t+1<NT),(t+1<NT));       ENDW(t);   RESC(); ROT();
;     STEP(pA0,pA1,pB0,pB1,t+1,(t+4<NT),(t+2<NT),(t+2<NT));     ENDW(t+1); RESC(); ROT();
.LBB0_1338:
	s_lshl_b32 s0, s86, 1
	v_add_u32_e32 v237, s0, v214
	ds_read_b64_tr_b16 v[192:193], v237 offset:24576
	v_xor_b32_e32 v64, 0x80000000, v235
	v_mov_b32_e32 v65, v64
	v_mov_b64_e32 v[66:67], v[64:65]
	v_mov_b64_e32 v[68:69], v[64:65]
	v_mov_b64_e32 v[70:71], v[64:65]
	v_mov_b64_e32 v[72:73], v[64:65]
	v_mov_b64_e32 v[74:75], v[64:65]
	v_mov_b64_e32 v[76:77], v[64:65]
	v_mov_b64_e32 v[78:79], v[64:65]
	v_add_f32_e32 v80, v112, v113
	v_add_f32_e32 v80, v114, v80
	v_add_f32_e32 v80, v115, v80
	v_add_f32_e32 v80, v116, v80
	v_add_f32_e32 v128, v117, v80
	s_waitcnt lgkmcnt(8)
	v_mfma_f32_32x32x16_bf16 v[80:95], v[188:191], v[156:159], v[64:79]
	v_cvt_pk_bf16_f32 v148, v112, v113
	v_cvt_pk_bf16_f32 v149, v114, v115
	ds_read_b64_tr_b16 v[194:195], v237 offset:25088
	s_waitcnt lgkmcnt(8)
	v_mfma_f32_32x32x16_bf16 v[64:79], v[184:187], v[156:159], v[64:79]
	v_add_f32_e32 v112, v118, v128
	v_add_f32_e32 v112, v119, v112
	v_add_f32_e32 v112, v120, v112
	v_add_f32_e32 v114, v121, v112
	v_cvt_pk_bf16_f32 v150, v116, v117
	v_cvt_pk_bf16_f32 v151, v118, v119
	ds_read_b64_tr_b16 v[112:113], v237 offset:28672
	s_waitcnt lgkmcnt(8)
	v_mfma_f32_32x32x16_bf16 v[80:95], v[180:183], v[152:155], v[80:95]
	v_add_f32_e32 v114, v122, v114
	v_add_f32_e32 v114, v123, v114
	v_add_f32_e32 v114, v124, v114
	v_add_f32_e32 v116, v125, v114
	v_cvt_pk_bf16_f32 v140, v120, v121
	v_cvt_pk_bf16_f32 v141, v122, v123
	ds_read_b64_tr_b16 v[114:115], v237 offset:29184
	s_waitcnt lgkmcnt(8)
	v_mfma_f32_32x32x16_bf16 v[64:79], v[176:179], v[152:155], v[64:79]
	v_add_f32_e32 v116, v126, v116
	v_add_f32_e32 v116, v127, v116
	v_add_f32_e32 v116, v96, v116
	v_add_f32_e32 v118, v97, v116
	v_cvt_pk_bf16_f32 v142, v124, v125
	v_cvt_pk_bf16_f32 v143, v126, v127
	ds_read_b64_tr_b16 v[116:117], v237 offset:32768
	s_waitcnt lgkmcnt(8)
	v_mfma_f32_32x32x16_bf16 v[80:95], v[172:175], v[144:147], v[80:95]
	v_add_f32_e32 v118, v98, v118
	v_add_f32_e32 v118, v99, v118
	v_add_f32_e32 v118, v100, v118
	v_add_f32_e32 v120, v101, v118
	v_cvt_pk_bf16_f32 v132, v96, v97
	v_cvt_pk_bf16_f32 v133, v98, v99
	ds_read_b64_tr_b16 v[118:119], v237 offset:33280
	s_waitcnt lgkmcnt(8)
	v_mfma_f32_32x32x16_bf16 v[64:79], v[168:171], v[144:147], v[64:79]
	v_add_f32_e32 v96, v102, v120
	v_add_f32_e32 v96, v103, v96
	v_add_f32_e32 v96, v104, v96
	v_add_f32_e32 v98, v105, v96
	v_cvt_pk_bf16_f32 v134, v100, v101
	v_cvt_pk_bf16_f32 v135, v102, v103
	ds_read_b64_tr_b16 v[96:97], v237 offset:36864
	s_waitcnt lgkmcnt(8)
	v_mfma_f32_32x32x16_bf16 v[80:95], v[164:167], v[136:139], v[80:95]
	v_add_f32_e32 v98, v106, v98
	v_add_f32_e32 v98, v107, v98
	v_add_f32_e32 v98, v108, v98
	v_add_f32_e32 v100, v109, v98
	v_cvt_pk_bf16_f32 v128, v104, v105
	v_cvt_pk_bf16_f32 v129, v106, v107
	ds_read_b64_tr_b16 v[98:99], v237 offset:37376
	s_waitcnt lgkmcnt(8)
	v_mfma_f32_32x32x16_bf16 v[64:79], v[160:163], v[136:139], v[64:79]
	v_add_f32_e32 v100, v110, v100
	v_add_f32_e32 v100, v111, v100
	v_add_f32_e32 v100, 0, v100
	v_cvt_pk_bf16_f32 v130, v108, v109
	v_cvt_pk_bf16_f32 v131, v110, v111
	s_add_i32 s19, s38, 2
	s_cmp_ge_i32 s19, s91
	s_cselect_b64 s[52:53], -1, 0
	s_and_b64 vcc, exec, s[52:53]
	s_cbranch_vccnz .LBB0_1340
	s_add_i32 s0, s18, s89
	s_mov_b32 s1, m0
	s_mov_b32 m0, s0
	s_nop 0
	global_load_lds_dwordx4 v[202:203], off
	s_mov_b32 m0, s1

;   #define RESC() do{ if(resc){ asm volatile("s_waitcnt lgkmcnt(0)":::"memory"); \
;       _Pragma("unroll") for(int d_=0;d_<4;++d_) _Pragma("unroll") for(int r=0;r<16;++r)o[d_][r]*=wsf[crow(r,hi)]; } }while(0)
; template<int THRL> __device__ __forceinline__ void attn_unit(int b,int hc,int qb,const bf16*Q,const bf16*__restrict__ K,const bf16*__restrict__ V,bf16*O,char*shm){
;     ...
;   STEP(pB0,pB1,pA0,pA1,NT-1,false,false,false); RESC();
.LBB0_1410:
	v_add_u32_e32 v202, s36, v214
	ds_read_b64_tr_b16 v[192:193], v202 offset:24576
	v_xor_b32_e32 v96, 0x80000000, v235
	v_mov_b32_e32 v97, v96
	v_mov_b64_e32 v[98:99], v[96:97]
	v_mov_b64_e32 v[100:101], v[96:97]
	v_mov_b64_e32 v[102:103], v[96:97]
	v_mov_b64_e32 v[104:105], v[96:97]
	v_mov_b64_e32 v[106:107], v[96:97]
	v_mov_b64_e32 v[108:109], v[96:97]
	v_mov_b64_e32 v[110:111], v[96:97]
	v_add_f32_e32 v112, v80, v81
	v_add_f32_e32 v112, v82, v112
	v_add_f32_e32 v112, v83, v112
	v_add_f32_e32 v112, v84, v112
	v_add_f32_e32 v128, v85, v112
	s_waitcnt lgkmcnt(8)
	v_mfma_f32_32x32x16_bf16 v[112:127], v[188:191], v[156:159], v[96:111]
	v_cvt_pk_bf16_f32 v148, v80, v81
	v_cvt_pk_bf16_f32 v149, v82, v83
	ds_read_b64_tr_b16 v[194:195], v202 offset:25088
	s_waitcnt lgkmcnt(8)
	v_mfma_f32_32x32x16_bf16 v[96:111], v[184:187], v[156:159], v[96:111]
	v_add_f32_e32 v80, v86, v128
	v_add_f32_e32 v80, v87, v80
	v_add_f32_e32 v80, v88, v80
	v_add_f32_e32 v82, v89, v80
	v_cvt_pk_bf16_f32 v150, v84, v85
	v_cvt_pk_bf16_f32 v151, v86, v87
	ds_read_b64_tr_b16 v[80:81], v202 offset:28672
	s_waitcnt lgkmcnt(8)
	v_mfma_f32_32x32x16_bf16 v[112:127], v[180:183], v[152:155], v[112:127]
	v_add_f32_e32 v82, v90, v82
	v_add_f32_e32 v82, v91, v82
	v_add_f32_e32 v82, v92, v82
	v_add_f32_e32 v84, v93, v82
	v_cvt_pk_bf16_f32 v140, v88, v89
	v_cvt_pk_bf16_f32 v141, v90, v91
	ds_read_b64_tr_b16 v[82:83], v202 offset:29184
	s_waitcnt lgkmcnt(8)
	v_mfma_f32_32x32x16_bf16 v[96:111], v[176:179], v[152:155], v[96:111]
	v_add_f32_e32 v84, v94, v84
	v_add_f32_e32 v84, v95, v84
	v_add_f32_e32 v84, v64, v84
	v_add_f32_e32 v86, v65, v84
	v_cvt_pk_bf16_f32 v142, v92, v93
	v_cvt_pk_bf16_f32 v143, v94, v95
	ds_read_b64_tr_b16 v[84:85], v202 offset:32768
	s_waitcnt lgkmcnt(8)
	v_mfma_f32_32x32x16_bf16 v[112:127], v[172:175], v[144:147], v[112:127]
	v_add_f32_e32 v86, v66, v86
	v_add_f32_e32 v86, v67, v86
	v_add_f32_e32 v86, v68, v86
	v_add_f32_e32 v88, v69, v86
	v_cvt_pk_bf16_f32 v132, v64, v65
	v_cvt_pk_bf16_f32 v133, v66, v67
	ds_read_b64_tr_b16 v[86:87], v202 offset:33280
	s_waitcnt lgkmcnt(8)
	v_mfma_f32_32x32x16_bf16 v[96:111], v[168:171], v[144:147], v[96:111]
	v_add_f32_e32 v64, v70, v88
	v_add_f32_e32 v64, v71, v64
	v_add_f32_e32 v64, v72, v64
	v_add_f32_e32 v66, v73, v64
	v_cvt_pk_bf16_f32 v134, v68, v69
	v_cvt_pk_bf16_f32 v135, v70, v71
	ds_read_b64_tr_b16 v[64:65], v202 offset:36864
	s_waitcnt lgkmcnt(8)
	v_mfma_f32_32x32x16_bf16 v[112:127], v[164:167], v[136:139], v[112:127]
	v_add_f32_e32 v66, v74, v66
	v_add_f32_e32 v66, v75, v66
	v_add_f32_e32 v66, v76, v66
	v_add_f32_e32 v68, v77, v66
	v_cvt_pk_bf16_f32 v128, v72, v73
	v_cvt_pk_bf16_f32 v129, v74, v75
	ds_read_b64_tr_b16 v[66:67], v202 offset:37376
	s_waitcnt lgkmcnt(8)
	v_mfma_f32_32x32x16_bf16 v[96:111], v[160:163], v[136:139], v[96:111]
	v_add_f32_e32 v68, v78, v68
	v_add_f32_e32 v68, v79, v68
	v_add_f32_e32 v68, 0, v68
	v_cvt_pk_bf16_f32 v130, v76, v77
	v_cvt_pk_bf16_f32 v131, v78, v79
	s_cmpk_gt_u32 s87, 0x2ff
	s_cbranch_scc1 .LBB0_1444
; __device__ __forceinline__ void cmask(f32x16&p0,f32x16&p1,int jb,int qrel,int hi,lds_cfptr bt){
;   const lds_cfptr t=bt+(qrel-64*jb-4*hi+256);
;   const int dq=qrel-64*jb-4*hi;
;   #pragma unroll
;   for(int r=0;r<16;++r){const int off=(r&3)+8*(r>>2); const float b0=t[-off],b1=t[-off-32]; p0[r]=(dq-off<0)?(p0[r]-INFINITY):p0[r]+b0; p1[r]=(dq-off-32<0)?(p1[r]-INFINITY):p1[r]+b1;}
; }
	v_sub_u32_e32 v69, v234, v215
	v_lshl_add_u32 v72, v69, 2, s70
	ds_read_b32 v70, v72 offset:128
	s_movk_i32 s0, 0xbf
	v_cmp_lt_i32_e32 vcc, s0, v69
	v_mov_b32_e32 v71, 0xff800000
	v_mov_b32_e32 v73, 0xff800000
	s_and_saveexec_b64 s[0:1], vcc
	v_readlane_b32 s36, v251, 4
	v_readlane_b32 s37, v251, 5
	ds_read_b32 v73, v72 offset:256
	s_or_b64 exec, exec, s[0:1]
	ds_read_b32 v74, v72 offset:124
	s_movk_i32 s0, 0xc0
	v_cmp_lt_i32_e32 vcc, s0, v69
	s_and_saveexec_b64 s[0:1], vcc
	ds_read_b32 v71, v72 offset:252
	s_or_b64 exec, exec, s[0:1]
	ds_read_b32 v75, v72 offset:120
	s_movk_i32 s0, 0xc1
	v_cmp_lt_i32_e32 vcc, s0, v69
	v_mov_b32_e32 v76, 0xff800000
	v_mov_b32_e32 v77, 0xff800000
	s_and_saveexec_b64 s[0:1], vcc
	ds_read_b32 v77, v72 offset:248
	s_or_b64 exec, exec, s[0:1]
	ds_read_b32 v78, v72 offset:116
	s_movk_i32 s0, 0xc2
	v_cmp_lt_i32_e32 vcc, s0, v69
	s_and_saveexec_b64 s[0:1], vcc
	ds_read_b32 v76, v72 offset:244
	s_or_b64 exec, exec, s[0:1]
	ds_read_b32 v79, v72 offset:96
	s_movk_i32 s0, 0xc7
	v_cmp_lt_i32_e32 vcc, s0, v69
	v_mov_b32_e32 v88, 0xff800000
	v_mov_b32_e32 v89, 0xff800000
	s_and_saveexec_b64 s[0:1], vcc
	ds_read_b32 v89, v72 offset:224
	s_or_b64 exec, exec, s[0:1]
	ds_read_b32 v90, v72 offset:92
	s_movk_i32 s0, 0xc8
	v_cmp_lt_i32_e32 vcc, s0, v69
	s_and_saveexec_b64 s[0:1], vcc
	ds_read_b32 v88, v72 offset:220
	s_or_b64 exec, exec, s[0:1]
	ds_read_b32 v91, v72 offset:88
	s_movk_i32 s0, 0xc9
	v_cmp_lt_i32_e32 vcc, s0, v69
	v_mov_b32_e32 v92, 0xff800000
	v_mov_b32_e32 v93, 0xff800000
	s_and_saveexec_b64 s[0:1], vcc
	ds_read_b32 v93, v72 offset:216
	s_or_b64 exec, exec, s[0:1]
	ds_read_b32 v94, v72 offset:84
	s_movk_i32 s0, 0xca
	v_cmp_lt_i32_e32 vcc, s0, v69
	s_and_saveexec_b64 s[0:1], vcc
	ds_read_b32 v92, v72 offset:212
	s_or_b64 exec, exec, s[0:1]
	ds_read_b32 v95, v72 offset:64
	s_movk_i32 s0, 0xcf
	v_cmp_lt_i32_e32 vcc, s0, v69
	v_mov_b32_e32 v136, 0xff800000
	v_mov_b32_e32 v137, 0xff800000
	s_and_saveexec_b64 s[0:1], vcc
	ds_read_b32 v137, v72 offset:192
	s_or_b64 exec, exec, s[0:1]
	ds_read_b32 v138, v72 offset:60
	s_movk_i32 s0, 0xd0
	v_cmp_lt_i32_e32 vcc, s0, v69
	s_and_saveexec_b64 s[0:1], vcc
	ds_read_b32 v136, v72 offset:188
	s_or_b64 exec, exec, s[0:1]
	ds_read_b32 v139, v72 offset:56
	s_movk_i32 s0, 0xd1
	v_cmp_lt_i32_e32 vcc, s0, v69
	v_mov_b32_e32 v144, 0xff800000
	v_mov_b32_e32 v145, 0xff800000
	s_and_saveexec_b64 s[0:1], vcc
	ds_read_b32 v145, v72 offset:184
	s_or_b64 exec, exec, s[0:1]
	ds_read_b32 v146, v72 offset:52
	s_movk_i32 s0, 0xd2
	v_cmp_lt_i32_e32 vcc, s0, v69
	s_and_saveexec_b64 s[0:1], vcc
	ds_read_b32 v144, v72 offset:180
	s_or_b64 exec, exec, s[0:1]
	ds_read_b32 v147, v72 offset:32
	s_movk_i32 s0, 0xd7
	v_cmp_lt_i32_e32 vcc, s0, v69
	v_mov_b32_e32 v152, 0xff800000
	v_mov_b32_e32 v153, 0xff800000
	s_and_saveexec_b64 s[0:1], vcc
	ds_read_b32 v153, v72 offset:160
	s_or_b64 exec, exec, s[0:1]
	ds_read_b32 v154, v72 offset:28
	s_movk_i32 s0, 0xd8
	v_cmp_lt_i32_e32 vcc, s0, v69
	s_and_saveexec_b64 s[0:1], vcc
	ds_read_b32 v152, v72 offset:156
	s_or_b64 exec, exec, s[0:1]
	ds_read_b32 v156, v72 offset:24
	s_movk_i32 s0, 0xd9
	v_cmp_lt_i32_e32 vcc, s0, v69
	v_mov_b32_e32 v157, 0xff800000
	v_mov_b32_e32 v158, 0xff800000
	s_and_saveexec_b64 s[0:1], vcc
	ds_read_b32 v158, v72 offset:152
	s_or_b64 exec, exec, s[0:1]
	ds_read_b32 v155, v72 offset:20
	s_movk_i32 s0, 0xda
	v_cmp_lt_i32_e32 vcc, s0, v69
	s_and_saveexec_b64 s[0:1], vcc
	ds_read_b32 v157, v72 offset:148
	s_or_b64 exec, exec, s[0:1]
	s_movk_i32 s0, 0xdf
	v_cmp_lt_i32_e32 vcc, s0, v69
	s_movk_i32 s0, 0xe0
	s_waitcnt lgkmcnt(14)
	v_add_f32_e32 v112, v112, v73
	v_cndmask_b32_e32 v70, v232, v70, vcc
	v_cmp_lt_i32_e32 vcc, s0, v69
	s_movk_i32 s0, 0xe1
	v_add_f32_e32 v96, v96, v70
	v_cndmask_b32_e32 v70, v232, v74, vcc
	v_cmp_lt_i32_e32 vcc, s0, v69
	s_movk_i32 s0, 0xe2
	v_add_f32_e32 v97, v97, v70
	s_waitcnt lgkmcnt(13)
	v_cndmask_b32_e32 v70, v232, v75, vcc
	v_cmp_lt_i32_e32 vcc, s0, v69
	s_movk_i32 s0, 0xe7
	v_add_f32_e32 v98, v98, v70
	s_waitcnt lgkmcnt(12)
	v_cndmask_b32_e32 v70, v232, v78, vcc
	v_cmp_lt_i32_e32 vcc, s0, v69
	s_movk_i32 s0, 0xe8
	v_add_f32_e32 v99, v99, v70
	s_waitcnt lgkmcnt(11)
	v_cndmask_b32_e32 v70, v232, v79, vcc
	v_cmp_lt_i32_e32 vcc, s0, v69
	s_movk_i32 s0, 0xe9
	v_add_f32_e32 v100, v100, v70
	s_waitcnt lgkmcnt(10)
	v_cndmask_b32_e32 v70, v232, v90, vcc
	v_cmp_lt_i32_e32 vcc, s0, v69
	s_movk_i32 s0, 0xea
	v_add_f32_e32 v101, v101, v70
	s_waitcnt lgkmcnt(9)
	v_cndmask_b32_e32 v70, v232, v91, vcc
	v_cmp_lt_i32_e32 vcc, s0, v69
	v_add_f32_e32 v102, v102, v70
	v_add_f32_e32 v113, v113, v71
	s_waitcnt lgkmcnt(8)
	v_cndmask_b32_e32 v70, v232, v94, vcc
	v_cmp_lt_i32_e32 vcc, s72, v69
	v_add_f32_e32 v103, v103, v70
	v_add_f32_e32 v114, v114, v77
	s_waitcnt lgkmcnt(7)
	v_cndmask_b32_e32 v70, v232, v95, vcc
	v_cmp_lt_i32_e32 vcc, s73, v69
	v_add_f32_e32 v104, v104, v70
	v_add_f32_e32 v115, v115, v76
	s_waitcnt lgkmcnt(6)
	v_cndmask_b32_e32 v70, v232, v138, vcc
	v_cmp_lt_i32_e32 vcc, s74, v69
	v_add_f32_e32 v105, v105, v70
	v_add_f32_e32 v116, v116, v89
	s_waitcnt lgkmcnt(5)
	v_cndmask_b32_e32 v70, v232, v139, vcc
	v_cmp_lt_i32_e32 vcc, s75, v69
	v_add_f32_e32 v106, v106, v70
	v_add_f32_e32 v117, v117, v88
	s_waitcnt lgkmcnt(4)
	v_cndmask_b32_e32 v70, v232, v146, vcc
	v_cmp_lt_i32_e32 vcc, s76, v69
	v_add_f32_e32 v107, v107, v70
	v_add_f32_e32 v118, v118, v93
	s_waitcnt lgkmcnt(3)
	v_cndmask_b32_e32 v70, v232, v147, vcc
	v_cmp_lt_i32_e32 vcc, s77, v69
	v_add_f32_e32 v108, v108, v70
	v_add_f32_e32 v119, v119, v92
	s_waitcnt lgkmcnt(2)
	v_cndmask_b32_e32 v70, v232, v154, vcc
	v_cmp_lt_i32_e32 vcc, s78, v69
	v_add_f32_e32 v109, v109, v70
	v_add_f32_e32 v120, v120, v137
	s_waitcnt lgkmcnt(1)
	v_cndmask_b32_e32 v70, v232, v156, vcc
	v_cmp_lt_i32_e32 vcc, s79, v69
	v_add_f32_e32 v121, v121, v136
	v_add_f32_e32 v122, v122, v145
	s_waitcnt lgkmcnt(0)
	v_cndmask_b32_e32 v69, v232, v155, vcc
	v_add_f32_e32 v123, v123, v144
	v_add_f32_e32 v124, v124, v153
	v_add_f32_e32 v125, v125, v152
	v_add_f32_e32 v126, v126, v158
	v_add_f32_e32 v110, v110, v70
	v_add_f32_e32 v127, v127, v157
	v_add_f32_e32 v111, v111, v69
	s_branch .LBB0_1445
